# P7 tail: norm-gain and output-gate loads issued after the last MFMA of the unit instead of after the four statistics barriers
# speedup vs baseline: 1.0062x; 1.0046x over previous
; DI uint4 pk8(f32x4 a, f32x4 b) { return make_uint4(pk2(a[0], a[1]), pk2(a[2], a[3]), pk2(b[0], b[1]), pk2(b[2], b[3])); }
; DI void mlstm_out_unit(const Params& p, unsigned char* smem, const int tid, int u) {
;     ...
;     const float* gain = p.in[10];
;     float4 gg[2][2];
;     uint2 ogv[4][2];
;     const int ch_l = h * 256 + 64 * w + (lane >> 4) * 8;
; #pragma unroll
;     for (int k = 0; k < 2; ++k) { gg[k][0] = *(const float4*)(gain + ch_l + 32 * k); gg[k][1] = *(const float4*)(gain + ch_l + 32 * k + 4); }
; #pragma unroll
;     for (int ni = 0; ni < 4; ++ni)
; #pragma unroll
;         for (int k = 0; k < 2; ++k)
;             ogv[ni][k] = *(const uint2*)((const unsigned char*)og + ((size_t)b * 8192 + c * 64 + 16 * ni + (lane & 15)) * 1024 + ch_l + 32 * k);
; #pragma unroll
;     for (int ni = 0; ni < 4; ++ni) {
;         const int t = 16 * ni + (lane & 15);
;         const float mu = mean_s[t], rs = rstd_s[t];
;         const size_t tok = (size_t)b * 8192 + c * 64 + t;
; #pragma unroll
;         for (int k = 0; k < 2; ++k) {
;             const f32x4 o2a = un4u8(ogv[ni][k].x), o2b = un4u8(ogv[ni][k].y);
;             f32x4 oa, ob;
;             oa[0] = (acc[2 * k][ni][0] - mu) * rs * gg[k][0].x * o2a[0];
;             oa[1] = (acc[2 * k][ni][1] - mu) * rs * gg[k][0].y * o2a[1];
;             oa[2] = (acc[2 * k][ni][2] - mu) * rs * gg[k][0].z * o2a[2];
;             oa[3] = (acc[2 * k][ni][3] - mu) * rs * gg[k][0].w * o2a[3];
;             ob[0] = (acc[2 * k + 1][ni][0] - mu) * rs * gg[k][1].x * o2b[0];
;             ob[1] = (acc[2 * k + 1][ni][1] - mu) * rs * gg[k][1].y * o2b[1];
;             ob[2] = (acc[2 * k + 1][ni][2] - mu) * rs * gg[k][1].z * o2b[2];
;             ob[3] = (acc[2 * k + 1][ni][3] - mu) * rs * gg[k][1].w * o2b[3];
;             *(uint4*)(hm + tok * 1024 + ch_l + 32 * k) = pk8(oa, ob);
;         }
.LBB0_716:
	s_or_b64 exec, exec, s[86:87]
	v_ashrrev_i32_e32 v0, 9, v97
	v_lshlrev_b32_e32 v1, 8, v126
	s_movk_i32 s86, 0x300
	v_and_or_b32 v100, v1, s86, v136
	v_ashrrev_i32_e32 v1, 31, v0
	v_readlane_b32 s72, v254, 36
	v_lshlrev_b64 v[16:17], 13, v[0:1]
	v_readlane_b32 s73, v254, 37
	v_or_b32_e32 v59, v16, v139
	v_or_b32_e32 v16, v59, v104
	s_mov_b64 s[72:73], s[4:5]
	v_lshl_add_u64 v[0:1], s[72:73], 0, v[100:101]
	v_lshlrev_b64 v[2:3], 10, v[16:17]
	v_lshlrev_b32_e32 v8, 2, v100
	v_readlane_b32 s76, v254, 40
	v_readlane_b32 s77, v254, 41
	v_lshl_add_u64 v[22:23], v[0:1], 0, v[2:3]
	s_waitcnt lgkmcnt(0)
	s_barrier
	s_nop 1
	s_waitcnt vmcnt(0)
	v_mov_b64_e32 v[4:5], v[188:189]
	v_mov_b64_e32 v[6:7], v[190:191]
	v_mov_b64_e32 v[12:13], v[192:193]
	v_mov_b64_e32 v[14:15], v[194:195]
	v_mov_b64_e32 v[54:55], v[204:205]
	v_mov_b64_e32 v[90:91], v[206:207]
	v_add_u32_e32 v63, 0x800, v123
	ds_read2_b32 v[24:25], v63 offset0:128 offset1:144
	ds_read2_b32 v[26:27], v63 offset0:192 offset1:208
	v_mov_b64_e32 v[0:1], v[196:197]
	v_mov_b64_e32 v[2:3], v[198:199]
	s_nop 0
	v_mov_b64_e32 v[8:9], v[200:201]
	v_mov_b64_e32 v[10:11], v[202:203]
	v_readlane_b32 s86, v254, 50
	s_movk_i32 s86, 0x4000
	v_lshlrev_b64 v[130:131], 11, v[16:17]
	v_add_co_u32_e32 v20, vcc, s86, v22
	s_waitcnt lgkmcnt(1)
	v_sub_f32_e32 v16, v128, v24
	v_sub_f32_e32 v128, v21, v24
	v_addc_co_u32_e32 v21, vcc, 0, v23, vcc
	s_mov_b32 s86, 0x8000
	v_add_co_u32_e32 v28, vcc, s86, v22
	v_lshlrev_b32_e32 v100, 1, v100
	v_sub_f32_e32 v129, v29, v24
	v_addc_co_u32_e32 v29, vcc, 0, v23, vcc
	s_mov_b32 s86, 0xc000
	v_lshl_add_u64 v[18:19], s[68:69], 0, v[100:101]
	v_sub_f32_e32 v100, v70, v24
	v_sub_f32_e32 v94, v94, v24
	v_sub_f32_e32 v95, v95, v24
	v_add_co_u32_e32 v70, vcc, s86, v22
	v_sub_f32_e32 v126, v127, v24
	v_sub_f32_e32 v127, v71, v24
	v_addc_co_u32_e32 v71, vcc, 0, v23, vcc
	s_waitcnt lgkmcnt(0)
	v_mul_f32_e32 v139, v26, v94
	v_mul_f32_e32 v142, v26, v95
	v_mov_b64_e32 v[94:95], v[208:209]
	v_mov_b64_e32 v[132:133], v[210:211]
	v_mov_b64_e32 v[140:141], v[212:213]
	s_nop 0
	v_mov_b64_e32 v[28:29], v[214:215]
	s_nop 0
	v_mov_b64_e32 v[22:23], v[216:217]
	v_mov_b64_e32 v[20:21], v[218:219]
	v_mul_f32_e32 v100, v26, v100
	v_mul_f32_e32 v16, v26, v16
	v_mul_f32_e32 v126, v26, v126
	v_mul_f32_e32 v127, v26, v127
	v_sub_f32_e32 v69, v69, v24
	v_mul_f32_e32 v128, v26, v128
	v_mul_f32_e32 v69, v26, v69
	v_sub_f32_e32 v68, v68, v24
	v_mul_f32_e32 v68, v26, v68
	v_sub_f32_e32 v88, v88, v24
	v_sub_f32_e32 v67, v67, v25
	v_mul_f32_e32 v67, v27, v67
	v_mul_f32_e32 v88, v26, v88
	v_lshl_add_u64 v[130:131], v[18:19], 0, v[130:131]
	v_sub_f32_e32 v66, v66, v25
	v_mul_f32_e32 v66, v27, v66
	v_sub_f32_e32 v65, v65, v25
	v_mul_f32_e32 v65, v27, v65
	v_sub_f32_e32 v64, v64, v25
	v_mul_f32_e32 v64, v27, v64
	v_add_u32_e32 v97, s90, v97
	s_movk_i32 s86, 0x7ff
	v_cmp_lt_i32_e32 vcc, s86, v97
	s_or_b64 s[92:93], vcc, s[92:93]
	v_readlane_b32 s74, v254, 38
	v_readlane_b32 s75, v254, 39
	v_readlane_b32 s78, v254, 42
	v_readlane_b32 s79, v254, 43
	v_readlane_b32 s80, v254, 44
	v_readlane_b32 s81, v254, 45
	v_readlane_b32 s82, v254, 46
	v_readlane_b32 s83, v254, 47
	v_readlane_b32 s84, v254, 48
	v_readlane_b32 s85, v254, 49
	v_readlane_b32 s87, v254, 51
	v_mul_f32_e32 v126, v4, v126
	v_mul_f32_e32 v70, v13, v100
	v_mul_f32_e32 v71, v14, v139
	v_mul_f32_e32 v100, v15, v142
	v_cvt_f32_ubyte0_e32 v139, v54
	v_cvt_f32_ubyte1_e32 v142, v54
	v_cvt_f32_ubyte2_e32 v143, v54
	v_cvt_f32_ubyte3_e32 v54, v54
	v_cvt_f32_ubyte0_e32 v144, v55
	v_cvt_f32_ubyte1_e32 v145, v55
	v_mul_f32_e32 v143, 0x3b808081, v143
	v_mul_f32_e32 v54, 0x3b808081, v54
	v_mul_f32_e32 v16, v12, v16
	v_mul_f32_e32 v127, v5, v127
	v_mul_f32_e32 v139, 0x3b808081, v139
	v_mul_f32_e32 v144, 0x3b808081, v144
	v_mul_f32_e32 v145, 0x3b808081, v145
	v_mul_f32_e32 v71, v143, v71
	v_mul_f32_e32 v54, v54, v100
	v_cvt_f32_ubyte2_e32 v146, v55
	v_cvt_f32_ubyte3_e32 v55, v55
	v_mul_f32_e32 v16, v139, v16
	v_mul_f32_e32 v100, v144, v126
	v_mul_f32_e32 v139, v145, v127
	v_mul_f32_e32 v126, v26, v129
	v_cvt_pk_bf16_f32 v127, v71, v54
	v_cvt_f32_ubyte1_e32 v54, v90
	v_mul_f32_e32 v128, v6, v128
	v_mul_f32_e32 v142, 0x3b808081, v142
	v_mul_f32_e32 v146, 0x3b808081, v146
	v_mul_f32_e32 v55, 0x3b808081, v55
	v_mul_f32_e32 v126, v7, v126
	v_mul_f32_e32 v54, 0x3b808081, v54
	v_mul_f32_e32 v69, v9, v69
	v_mul_f32_e32 v70, v142, v70
	v_mul_f32_e32 v142, v146, v128
	v_mul_f32_e32 v55, v55, v126
	v_mul_f32_e32 v54, v54, v69
	v_sub_f32_e32 v69, v84, v24
	v_cvt_pk_bf16_f32 v129, v142, v55
	v_cvt_f32_ubyte2_e32 v55, v90
	v_mul_f32_e32 v69, v26, v69
	v_mul_f32_e32 v55, 0x3b808081, v55
	v_mul_f32_e32 v69, v10, v69
	v_mul_f32_e32 v55, v55, v69
	v_sub_f32_e32 v69, v86, v24
	v_cvt_pk_bf16_f32 v126, v16, v70
	v_cvt_f32_ubyte3_e32 v70, v90
	v_mul_f32_e32 v69, v26, v69
	v_mul_f32_e32 v70, 0x3b808081, v70
	v_mul_f32_e32 v69, v11, v69
	v_mul_f32_e32 v69, v70, v69
	v_sub_f32_e32 v70, v85, v24
	v_cvt_f32_ubyte0_e32 v16, v90
	v_cvt_f32_ubyte0_e32 v71, v91
	v_cvt_f32_ubyte1_e32 v90, v91
	v_mul_f32_e32 v70, v26, v70
	v_mul_f32_e32 v71, 0x3b808081, v71
	v_mul_f32_e32 v90, 0x3b808081, v90
	v_mul_f32_e32 v70, v0, v70
	v_mul_f32_e32 v68, v1, v68
	v_mul_f32_e32 v70, v71, v70
	v_mul_f32_e32 v71, v90, v68
	v_sub_f32_e32 v68, v81, v24
	v_sub_f32_e32 v24, v80, v24
	v_cvt_pk_bf16_f32 v128, v100, v139
	v_cvt_f32_ubyte2_e32 v100, v91
	v_cvt_f32_ubyte3_e32 v91, v91
	v_mul_f32_e32 v68, v26, v68
	v_mul_f32_e32 v24, v26, v24
	v_mul_f32_e32 v100, 0x3b808081, v100
	v_mul_f32_e32 v91, 0x3b808081, v91
	v_mul_f32_e32 v68, v2, v68
	v_mul_f32_e32 v24, v3, v24
	v_mul_f32_e32 v81, v100, v68
	v_mul_f32_e32 v24, v91, v24
; DI uint4 pk8(f32x4 a, f32x4 b) { return make_uint4(pk2(a[0], a[1]), pk2(a[2], a[3]), pk2(b[0], b[1]), pk2(b[2], b[3])); }
; DI void mlstm_out_unit(const Params& p, unsigned char* smem, const int tid, int u) {
;     ...
; #pragma unroll
;     for (int ni = 0; ni < 4; ++ni) {
;         const int t = 16 * ni + (lane & 15);
;         const float mu = mean_s[t], rs = rstd_s[t];
;         const size_t tok = (size_t)b * 8192 + c * 64 + t;
; #pragma unroll
;         for (int k = 0; k < 2; ++k) {
;             const f32x4 o2a = un4u8(ogv[ni][k].x), o2b = un4u8(ogv[ni][k].y);
;             f32x4 oa, ob;
;             oa[0] = (acc[2 * k][ni][0] - mu) * rs * gg[k][0].x * o2a[0];
;             oa[1] = (acc[2 * k][ni][1] - mu) * rs * gg[k][0].y * o2a[1];
;             oa[2] = (acc[2 * k][ni][2] - mu) * rs * gg[k][0].z * o2a[2];
;             oa[3] = (acc[2 * k][ni][3] - mu) * rs * gg[k][0].w * o2a[3];
;             ob[0] = (acc[2 * k + 1][ni][0] - mu) * rs * gg[k][1].x * o2b[0];
;             ob[1] = (acc[2 * k + 1][ni][1] - mu) * rs * gg[k][1].y * o2b[1];
;             ob[2] = (acc[2 * k + 1][ni][2] - mu) * rs * gg[k][1].z * o2b[2];
;             ob[3] = (acc[2 * k + 1][ni][3] - mu) * rs * gg[k][1].w * o2b[3];
;             *(uint4*)(hm + tok * 1024 + ch_l + 32 * k) = pk8(oa, ob);
;         }
	v_cvt_pk_bf16_f32 v70, v70, v71
	v_cvt_pk_bf16_f32 v71, v81, v24
	v_cvt_f32_ubyte1_e32 v24, v94
	v_mul_f32_e32 v24, 0x3b808081, v24
	v_mul_f32_e32 v67, v13, v67
	v_mul_f32_e32 v24, v24, v67
	v_sub_f32_e32 v67, v92, v25
	v_mul_f32_e32 v16, 0x3b808081, v16
	v_mul_f32_e32 v88, v8, v88
	v_cvt_f32_ubyte2_e32 v26, v94
	v_mul_f32_e32 v67, v27, v67
	v_mul_f32_e32 v16, v16, v88
	v_mul_f32_e32 v26, 0x3b808081, v26
	v_mul_f32_e32 v67, v14, v67
	v_cvt_pk_bf16_f32 v68, v16, v54
	v_cvt_pk_bf16_f32 v69, v55, v69
	v_mul_f32_e32 v26, v26, v67
	v_sub_f32_e32 v67, v89, v25
	global_store_dwordx4 v[130:131], v[68:71], off offset:64
	v_mul_f32_e32 v67, v27, v67
	v_mul_f32_e32 v67, v15, v67
	v_cvt_f32_ubyte3_e32 v68, v94
	v_mul_f32_e32 v68, 0x3b808081, v68
	v_mul_f32_e32 v67, v68, v67
	v_sub_f32_e32 v68, v87, v25
	v_cvt_f32_ubyte0_e32 v69, v95
	v_cvt_f32_ubyte1_e32 v70, v95
	v_mul_f32_e32 v68, v27, v68
	v_mul_f32_e32 v69, 0x3b808081, v69
	v_mul_f32_e32 v70, 0x3b808081, v70
	v_mul_f32_e32 v68, v4, v68
	v_mul_f32_e32 v66, v5, v66
	v_mul_f32_e32 v68, v69, v68
	v_mul_f32_e32 v69, v70, v66
	v_sub_f32_e32 v66, v83, v25
	v_cvt_f32_ubyte2_e32 v71, v95
	v_mul_f32_e32 v66, v27, v66
	v_or_b32_e32 v16, v59, v118
	v_mul_f32_e32 v71, 0x3b808081, v71
	v_sub_f32_e32 v81, v93, v25
	v_mul_f32_e32 v66, v6, v66
	v_lshlrev_b64 v[54:55], 11, v[16:17]
	v_cvt_f32_ubyte0_e32 v16, v94
	v_mul_f32_e32 v81, v27, v81
	v_mul_f32_e32 v70, v71, v66
	v_sub_f32_e32 v66, v82, v25
	v_mul_f32_e32 v16, 0x3b808081, v16
	v_cvt_f32_ubyte3_e32 v80, v95
	v_mul_f32_e32 v81, v12, v81
	v_mul_f32_e32 v66, v27, v66
	v_mul_f32_e32 v80, 0x3b808081, v80
	v_mul_f32_e32 v16, v16, v81
	v_mul_f32_e32 v66, v7, v66
	v_mul_f32_e32 v71, v80, v66
	v_cvt_pk_bf16_f32 v66, v16, v24
	v_cvt_f32_ubyte1_e32 v24, v132
	v_mul_f32_e32 v24, 0x3b808081, v24
	v_mul_f32_e32 v65, v9, v65
	v_mul_f32_e32 v24, v24, v65
	v_sub_f32_e32 v65, v75, v25
	v_cvt_pk_bf16_f32 v67, v26, v67
	v_cvt_f32_ubyte2_e32 v26, v132
	v_mul_f32_e32 v65, v27, v65
	v_mul_f32_e32 v26, 0x3b808081, v26
	v_mul_f32_e32 v65, v10, v65
	v_lshl_add_u64 v[54:55], v[18:19], 0, v[54:55]
	v_cvt_pk_bf16_f32 v68, v68, v69
	v_cvt_pk_bf16_f32 v69, v70, v71
	v_mul_f32_e32 v26, v26, v65
	v_sub_f32_e32 v65, v76, v25
	global_store_dwordx4 v[54:55], v[66:69], off
	v_mul_f32_e32 v65, v27, v65
	v_mul_f32_e32 v65, v11, v65
	v_cvt_f32_ubyte3_e32 v66, v132
	v_mul_f32_e32 v66, 0x3b808081, v66
	v_mul_f32_e32 v65, v66, v65
	v_sub_f32_e32 v66, v74, v25
	v_cvt_f32_ubyte0_e32 v67, v133
	v_mul_f32_e32 v66, v27, v66
	v_mul_f32_e32 v67, 0x3b808081, v67
	v_mul_f32_e32 v66, v0, v66
	v_sub_f32_e32 v71, v78, v25
	v_mul_f32_e32 v66, v67, v66
	v_sub_f32_e32 v67, v73, v25
	v_sub_f32_e32 v25, v72, v25
	v_cvt_f32_ubyte0_e32 v16, v132
	v_cvt_f32_ubyte1_e32 v68, v133
	v_cvt_f32_ubyte2_e32 v69, v133
	v_cvt_f32_ubyte3_e32 v70, v133
	v_mul_f32_e32 v71, v27, v71
	v_mul_f32_e32 v67, v27, v67
	v_mul_f32_e32 v25, v27, v25
	v_mul_f32_e32 v16, 0x3b808081, v16
	v_mul_f32_e32 v68, 0x3b808081, v68
	v_mul_f32_e32 v69, 0x3b808081, v69
	v_mul_f32_e32 v70, 0x3b808081, v70
	v_mul_f32_e32 v71, v8, v71
	v_mul_f32_e32 v64, v1, v64
	v_mul_f32_e32 v67, v2, v67
	v_mul_f32_e32 v25, v3, v25
	v_mul_f32_e32 v16, v16, v71
	v_mul_f32_e32 v64, v68, v64
	v_mul_f32_e32 v67, v69, v67
	v_mul_f32_e32 v27, v70, v25
	v_cvt_pk_bf16_f32 v24, v16, v24
	v_cvt_pk_bf16_f32 v25, v26, v65
	v_cvt_pk_bf16_f32 v26, v66, v64
	v_cvt_pk_bf16_f32 v27, v67, v27
	global_store_dwordx4 v[130:131], v[126:129], off
	global_store_dwordx4 v[54:55], v[24:27], off offset:64
	ds_read2_b32 v[54:55], v63 offset0:160 offset1:176
	ds_read2_b32 v[64:65], v63 offset0:224 offset1:240
	v_or_b32_e32 v16, v59, v120
	v_lshlrev_b64 v[24:25], 11, v[16:17]
	v_lshl_add_u64 v[66:67], v[18:19], 0, v[24:25]
	s_waitcnt lgkmcnt(1)
	v_sub_f32_e32 v61, v61, v54
	v_cvt_f32_ubyte1_e32 v24, v140
	s_waitcnt lgkmcnt(0)
; DI uint4 pk8(f32x4 a, f32x4 b) { return make_uint4(pk2(a[0], a[1]), pk2(a[2], a[3]), pk2(b[0], b[1]), pk2(b[2], b[3])); }
; DI void mlstm_out_unit(const Params& p, unsigned char* smem, const int tid, int u) {
;     ...
; #pragma unroll
;     for (int ni = 0; ni < 4; ++ni) {
;         const int t = 16 * ni + (lane & 15);
;         const float mu = mean_s[t], rs = rstd_s[t];
;         const size_t tok = (size_t)b * 8192 + c * 64 + t;
; #pragma unroll
;         for (int k = 0; k < 2; ++k) {
;             const f32x4 o2a = un4u8(ogv[ni][k].x), o2b = un4u8(ogv[ni][k].y);
;             f32x4 oa, ob;
;             oa[0] = (acc[2 * k][ni][0] - mu) * rs * gg[k][0].x * o2a[0];
;             oa[1] = (acc[2 * k][ni][1] - mu) * rs * gg[k][0].y * o2a[1];
;             oa[2] = (acc[2 * k][ni][2] - mu) * rs * gg[k][0].z * o2a[2];
;             oa[3] = (acc[2 * k][ni][3] - mu) * rs * gg[k][0].w * o2a[3];
;             ob[0] = (acc[2 * k + 1][ni][0] - mu) * rs * gg[k][1].x * o2b[0];
;             ob[1] = (acc[2 * k + 1][ni][1] - mu) * rs * gg[k][1].y * o2b[1];
;             ob[2] = (acc[2 * k + 1][ni][2] - mu) * rs * gg[k][1].z * o2b[2];
;             ob[3] = (acc[2 * k + 1][ni][3] - mu) * rs * gg[k][1].w * o2b[3];
;             *(uint4*)(hm + tok * 1024 + ch_l + 32 * k) = pk8(oa, ob);
;         }
;     }
;     __syncthreads();
; }
	v_mul_f32_e32 v61, v64, v61
	v_mul_f32_e32 v24, 0x3b808081, v24
	v_mul_f32_e32 v61, v13, v61
	v_mul_f32_e32 v24, v24, v61
	v_sub_f32_e32 v61, v77, v54
	v_cvt_f32_ubyte2_e32 v25, v140
	v_mul_f32_e32 v61, v64, v61
	v_mul_f32_e32 v25, 0x3b808081, v25
	v_mul_f32_e32 v61, v14, v61
	v_sub_f32_e32 v70, v79, v54
	v_mul_f32_e32 v25, v25, v61
	v_sub_f32_e32 v61, v62, v54
	v_sub_f32_e32 v60, v60, v54
	v_sub_f32_e32 v57, v57, v54
	v_sub_f32_e32 v58, v58, v54
	v_sub_f32_e32 v56, v56, v54
	v_cvt_f32_ubyte0_e32 v16, v140
	v_cvt_f32_ubyte3_e32 v26, v140
	v_cvt_f32_ubyte0_e32 v27, v141
	v_cvt_f32_ubyte1_e32 v63, v141
	v_cvt_f32_ubyte2_e32 v68, v141
	v_cvt_f32_ubyte3_e32 v69, v141
	v_mul_f32_e32 v70, v64, v70
	v_mul_f32_e32 v61, v64, v61
	v_mul_f32_e32 v60, v64, v60
	v_mul_f32_e32 v57, v64, v57
	v_mul_f32_e32 v58, v64, v58
	v_mul_f32_e32 v56, v64, v56
	v_mul_f32_e32 v16, 0x3b808081, v16
	v_mul_f32_e32 v26, 0x3b808081, v26
	v_mul_f32_e32 v27, 0x3b808081, v27
	v_mul_f32_e32 v63, 0x3b808081, v63
	v_mul_f32_e32 v68, 0x3b808081, v68
	v_mul_f32_e32 v69, 0x3b808081, v69
	v_mul_f32_e32 v70, v12, v70
	v_mul_f32_e32 v61, v15, v61
	v_mul_f32_e32 v60, v4, v60
	v_mul_f32_e32 v57, v5, v57
	v_mul_f32_e32 v58, v6, v58
	v_mul_f32_e32 v56, v7, v56
	v_mul_f32_e32 v16, v16, v70
	v_mul_f32_e32 v26, v26, v61
	v_mul_f32_e32 v27, v27, v60
	v_mul_f32_e32 v57, v63, v57
	v_mul_f32_e32 v58, v68, v58
	v_mul_f32_e32 v56, v69, v56
	v_sub_f32_e32 v52, v52, v54
	v_cvt_pk_bf16_f32 v24, v16, v24
	v_cvt_pk_bf16_f32 v25, v25, v26
	v_cvt_pk_bf16_f32 v26, v27, v57
	v_cvt_pk_bf16_f32 v27, v58, v56
	v_cvt_f32_ubyte0_e32 v16, v28
	v_mul_f32_e32 v52, v64, v52
	v_sub_f32_e32 v44, v44, v54
	v_sub_f32_e32 v43, v43, v54
	global_store_dwordx4 v[66:67], v[24:27], off
	v_mul_f32_e32 v16, 0x3b808081, v16
	v_mul_f32_e32 v52, v8, v52
	v_cvt_f32_ubyte2_e32 v25, v28
	v_cvt_f32_ubyte0_e32 v27, v29
	v_mul_f32_e32 v44, v64, v44
	v_mul_f32_e32 v43, v64, v43
	v_mul_f32_e32 v25, 0x3b808081, v25
	v_mul_f32_e32 v27, 0x3b808081, v27
	v_mul_f32_e32 v16, v16, v52
	v_sub_f32_e32 v52, v53, v54
	v_mul_f32_e32 v44, v10, v44
	v_mul_f32_e32 v43, v0, v43
	v_cvt_f32_ubyte1_e32 v24, v28
	v_mul_f32_e32 v52, v64, v52
	v_mul_f32_e32 v25, v25, v44
	v_sub_f32_e32 v44, v46, v54
	v_mul_f32_e32 v27, v27, v43
	v_sub_f32_e32 v43, v49, v54
	v_mul_f32_e32 v24, 0x3b808081, v24
	v_cvt_f32_ubyte3_e32 v26, v28
	v_cvt_f32_ubyte1_e32 v28, v29
	v_mul_f32_e32 v52, v9, v52
	v_mul_f32_e32 v44, v64, v44
	v_mul_f32_e32 v43, v64, v43
	v_mul_f32_e32 v26, 0x3b808081, v26
	v_mul_f32_e32 v28, 0x3b808081, v28
	v_mul_f32_e32 v24, v24, v52
	v_mul_f32_e32 v44, v11, v44
	v_mul_f32_e32 v43, v1, v43
	v_mul_f32_e32 v26, v26, v44
	v_mul_f32_e32 v28, v28, v43
	v_cvt_pk_bf16_f32 v24, v16, v24
	v_or_b32_e32 v16, v59, v122
	v_cvt_pk_bf16_f32 v25, v25, v26
	v_cvt_pk_bf16_f32 v26, v27, v28
	v_lshlrev_b64 v[16:17], 11, v[16:17]
	v_sub_f32_e32 v28, v51, v55
	v_lshl_add_u64 v[16:17], v[18:19], 0, v[16:17]
	v_cvt_f32_ubyte0_e32 v18, v22
	v_mul_f32_e32 v28, v65, v28
	v_mul_f32_e32 v18, 0x3b808081, v18
	v_mul_f32_e32 v12, v12, v28
	v_mul_f32_e32 v12, v18, v12
	v_sub_f32_e32 v18, v45, v55
	v_mul_f32_e32 v18, v65, v18
	v_sub_f32_e32 v42, v42, v54
	v_sub_f32_e32 v40, v40, v54
	v_mul_f32_e32 v13, v13, v18
	v_sub_f32_e32 v18, v50, v55
	v_cvt_f32_ubyte2_e32 v56, v29
	v_cvt_f32_ubyte3_e32 v29, v29
	v_mul_f32_e32 v42, v64, v42
	v_mul_f32_e32 v40, v64, v40
	v_mul_f32_e32 v18, v65, v18
	v_mul_f32_e32 v56, 0x3b808081, v56
	v_mul_f32_e32 v29, 0x3b808081, v29
	v_mul_f32_e32 v42, v2, v42
	v_mul_f32_e32 v40, v3, v40
	v_mul_f32_e32 v14, v14, v18
	v_sub_f32_e32 v18, v48, v55
	v_mul_f32_e32 v42, v56, v42
	v_mul_f32_e32 v29, v29, v40
	v_mul_f32_e32 v18, v65, v18
	v_cvt_pk_bf16_f32 v27, v42, v29
	v_mul_f32_e32 v15, v15, v18
	v_sub_f32_e32 v18, v47, v55
	global_store_dwordx4 v[66:67], v[24:27], off offset:64
	v_mul_f32_e32 v18, v65, v18
	v_mul_f32_e32 v4, v4, v18
	v_cvt_f32_ubyte0_e32 v25, v23
	v_mul_f32_e32 v25, 0x3b808081, v25
	v_mul_f32_e32 v18, v25, v4
	v_sub_f32_e32 v4, v41, v55
	v_cvt_f32_ubyte1_e32 v19, v22
	v_cvt_f32_ubyte1_e32 v26, v23
	v_mul_f32_e32 v4, v65, v4
	v_mul_f32_e32 v19, 0x3b808081, v19
	v_mul_f32_e32 v26, 0x3b808081, v26
	v_mul_f32_e32 v4, v5, v4
	v_mul_f32_e32 v13, v19, v13
	v_mul_f32_e32 v19, v26, v4
	v_sub_f32_e32 v4, v39, v55
	v_cvt_f32_ubyte2_e32 v24, v22
	v_cvt_f32_ubyte3_e32 v22, v22
	v_cvt_f32_ubyte2_e32 v27, v23
	v_mul_f32_e32 v4, v65, v4
	v_mul_f32_e32 v22, 0x3b808081, v22
	v_mul_f32_e32 v27, 0x3b808081, v27
	v_mul_f32_e32 v4, v6, v4
	v_mul_f32_e32 v15, v22, v15
	v_mul_f32_e32 v22, v27, v4
	v_sub_f32_e32 v4, v38, v55
	v_cvt_f32_ubyte3_e32 v23, v23
	v_mul_f32_e32 v4, v65, v4
	v_mul_f32_e32 v24, 0x3b808081, v24
	v_mul_f32_e32 v23, 0x3b808081, v23
	v_mul_f32_e32 v4, v7, v4
	v_mul_f32_e32 v14, v24, v14
	v_mul_f32_e32 v7, v23, v4
	v_cvt_pk_bf16_f32 v4, v12, v13
	v_cvt_pk_bf16_f32 v5, v14, v15
	v_cvt_pk_bf16_f32 v6, v18, v19
	v_cvt_pk_bf16_f32 v7, v22, v7
	v_sub_f32_e32 v18, v36, v55
	global_store_dwordx4 v[16:17], v[4:7], off
	v_mul_f32_e32 v18, v65, v18
	v_mul_f32_e32 v8, v8, v18
	v_cvt_f32_ubyte0_e32 v4, v20
	v_mul_f32_e32 v4, 0x3b808081, v4
	v_mul_f32_e32 v4, v4, v8
	v_sub_f32_e32 v8, v37, v55
	v_cvt_f32_ubyte1_e32 v5, v20
	v_mul_f32_e32 v8, v65, v8
	v_mul_f32_e32 v5, 0x3b808081, v5
	v_mul_f32_e32 v8, v9, v8
	v_mul_f32_e32 v5, v5, v8
	v_sub_f32_e32 v8, v34, v55
	v_cvt_f32_ubyte2_e32 v6, v20
	v_mul_f32_e32 v8, v65, v8
	v_mul_f32_e32 v6, 0x3b808081, v6
	v_mul_f32_e32 v8, v10, v8
	v_mul_f32_e32 v6, v6, v8
	v_sub_f32_e32 v8, v35, v55
	v_cvt_f32_ubyte3_e32 v7, v20
	v_mul_f32_e32 v8, v65, v8
	v_mul_f32_e32 v7, 0x3b808081, v7
	v_mul_f32_e32 v8, v11, v8
	v_mul_f32_e32 v7, v7, v8
	v_sub_f32_e32 v8, v32, v55
	v_cvt_f32_ubyte0_e32 v12, v21
	v_mul_f32_e32 v8, v65, v8
	v_mul_f32_e32 v12, 0x3b808081, v12
	v_mul_f32_e32 v0, v0, v8
	v_mul_f32_e32 v8, v12, v0
	v_sub_f32_e32 v0, v33, v55
	v_cvt_f32_ubyte1_e32 v13, v21
	v_mul_f32_e32 v0, v65, v0
	v_mul_f32_e32 v13, 0x3b808081, v13
	v_mul_f32_e32 v0, v1, v0
	v_mul_f32_e32 v9, v13, v0
	v_sub_f32_e32 v0, v31, v55
	v_cvt_f32_ubyte2_e32 v14, v21
	v_mul_f32_e32 v0, v65, v0
	v_mul_f32_e32 v14, 0x3b808081, v14
	v_mul_f32_e32 v0, v2, v0
	v_mul_f32_e32 v10, v14, v0
	v_sub_f32_e32 v0, v30, v55
	v_cvt_f32_ubyte3_e32 v15, v21
	v_mul_f32_e32 v0, v65, v0
	v_mul_f32_e32 v15, 0x3b808081, v15
	v_mul_f32_e32 v0, v3, v0
	v_mul_f32_e32 v3, v15, v0
	v_cvt_pk_bf16_f32 v0, v4, v5
	v_cvt_pk_bf16_f32 v1, v6, v7
	v_cvt_pk_bf16_f32 v2, v8, v9
	v_cvt_pk_bf16_f32 v3, v10, v3
	global_store_dwordx4 v[16:17], v[0:3], off offset:64
	s_barrier
	s_andn2_b64 exec, exec, s[92:93]
	s_cbranch_execz .LBB0_783

; DI uint2 pk4(f32x4 v) { return make_uint2(pk2(v[0], v[1]), pk2(v[2], v[3])); }
; DI f32x4 mfma16(bf16x8 a, bf16x8 b, f32x4 c) { return __builtin_amdgcn_mfma_f32_16x16x32_bf16(a, b, c, 0, 0, 0); }
; DI void mlstm_out_unit(const Params& p, unsigned char* smem, const int tid, int u) {
;     ...
;         for (int pr = 0; pr < 2; ++pr) {
;             uint2 lo = pk4(X[2 * pr]), hi = pk4(X[2 * pr + 1]);
;             xs[(w * 2 + pr) * 64 + lane] = make_uint4(lo.x, lo.y, hi.x, hi.y);
;         }
;     }
;     __syncthreads();
;     f32x4 acc[4][4];
; #pragma unroll
;     for (int i = 0; i < 4; ++i)
; #pragma unroll
;         for (int j = 0; j < 4; ++j) acc[i][j] = f32x4{0.f, 0.f, 0.f, 0.f};
;     {
;         const bf16_t* qb = q + (tok0 + (lane & 15)) * 128 + (lane >> 4) * 8;
; #pragma unroll
;         for (int ks = 0; ks < 4; ++ks) {
;             bf16x8 bfr[4];
; #pragma unroll
;             for (int i = 0; i < 4; ++i) bfr[i] = ld16(qb + (size_t)i * 16 * 128 + ks * 32);
; #pragma unroll
;             for (int i = 0; i < 4; ++i)
; #pragma unroll
;                 for (int j = 0; j < 4; ++j) acc[i][j] = mfma16(ctf[ks][i], bfr[j], acc[i][j]);
;         }
;     }
.LBB0_763:
	s_or_b64 exec, exec, s[86:87]
	v_lshl_add_u64 v[180:181], v[112:113], 0, v[130:131]
	v_add_co_u32_e32 v84, vcc, s3, v180
	s_movk_i32 s86, 0x3000
	s_nop 0
	v_addc_co_u32_e32 v85, vcc, 0, v181, vcc
	v_add_co_u32_e32 v86, vcc, s91, v180
	v_cvt_pk_bf16_f32 v80, v81, v80
	s_nop 0
	v_addc_co_u32_e32 v87, vcc, 0, v181, vcc
	v_add_co_u32_e32 v88, vcc, s86, v180
	v_cvt_pk_bf16_f32 v81, v77, v76
	v_cvt_pk_bf16_f32 v82, v79, v78
	v_cvt_pk_bf16_f32 v83, v73, v72
	v_cvt_pk_bf16_f32 v66, v75, v74
	s_waitcnt lgkmcnt(0)
	v_cvt_pk_bf16_f32 v67, v69, v68
	v_cvt_pk_bf16_f32 v68, v71, v70
	v_cvt_pk_bf16_f32 v69, v65, v64
	v_addc_co_u32_e32 v89, vcc, 0, v181, vcc
	ds_write_b128 v121, v[80:83] offset:4096
	ds_write_b128 v121, v[66:69] offset:5120
	s_waitcnt lgkmcnt(0)
	s_barrier
	s_waitcnt vmcnt(0)
	v_mov_b64_e32 v[64:65], v[188:189]
	v_mov_b64_e32 v[66:67], v[190:191]
	v_mov_b64_e32 v[68:69], v[192:193]
	v_mov_b64_e32 v[70:71], v[194:195]
	v_mov_b64_e32 v[72:73], v[196:197]
	v_mov_b64_e32 v[74:75], v[198:199]
	v_mov_b64_e32 v[76:77], v[200:201]
	v_mov_b64_e32 v[78:79], v[202:203]
	s_waitcnt vmcnt(3)
	v_mfma_f32_16x16x32_bf16 v[80:83], v[52:55], v[64:67], 0
	s_waitcnt vmcnt(2)
	v_mfma_f32_16x16x32_bf16 v[92:95], v[52:55], v[68:71], 0
	s_waitcnt vmcnt(1)
	v_mfma_f32_16x16x32_bf16 v[130:133], v[52:55], v[72:75], 0
	s_waitcnt vmcnt(0)
	v_mfma_f32_16x16x32_bf16 v[52:55], v[52:55], v[76:79], 0
	v_mfma_f32_16x16x32_bf16 v[140:143], v[60:63], v[64:67], 0
	v_mfma_f32_16x16x32_bf16 v[144:147], v[60:63], v[68:71], 0
	v_mfma_f32_16x16x32_bf16 v[148:151], v[60:63], v[72:75], 0
	v_mfma_f32_16x16x32_bf16 v[60:63], v[60:63], v[76:79], 0
	v_mfma_f32_16x16x32_bf16 v[152:155], v[56:59], v[64:67], 0
	v_mfma_f32_16x16x32_bf16 v[156:159], v[56:59], v[68:71], 0
	v_mfma_f32_16x16x32_bf16 v[160:163], v[56:59], v[72:75], 0
	v_mfma_f32_16x16x32_bf16 v[56:59], v[56:59], v[76:79], 0
	v_mfma_f32_16x16x32_bf16 v[64:67], v[48:51], v[64:67], 0
	v_mfma_f32_16x16x32_bf16 v[68:71], v[48:51], v[68:71], 0
	v_mfma_f32_16x16x32_bf16 v[72:75], v[48:51], v[72:75], 0
	v_mfma_f32_16x16x32_bf16 v[48:51], v[48:51], v[76:79], 0
	v_mov_b64_e32 v[76:77], v[204:205]
	v_mov_b64_e32 v[78:79], v[206:207]
	v_mov_b64_e32 v[164:165], v[208:209]
	v_mov_b64_e32 v[166:167], v[210:211]
	v_mov_b64_e32 v[168:169], v[212:213]
	v_mov_b64_e32 v[170:171], v[214:215]
	v_mov_b64_e32 v[172:173], v[216:217]
	v_mov_b64_e32 v[174:175], v[218:219]
	s_waitcnt vmcnt(3)
	v_mfma_f32_16x16x32_bf16 v[80:83], v[44:47], v[76:79], v[80:83]
	s_waitcnt vmcnt(2)
	v_mfma_f32_16x16x32_bf16 v[92:95], v[44:47], v[164:167], v[92:95]
	s_waitcnt vmcnt(1)
	v_mfma_f32_16x16x32_bf16 v[130:133], v[44:47], v[168:171], v[130:133]
	s_waitcnt vmcnt(0)
	v_mfma_f32_16x16x32_bf16 v[44:47], v[44:47], v[172:175], v[52:55]
	v_mfma_f32_16x16x32_bf16 v[52:55], v[40:43], v[76:79], v[140:143]
	v_mfma_f32_16x16x32_bf16 v[140:143], v[40:43], v[164:167], v[144:147]
	v_mfma_f32_16x16x32_bf16 v[144:147], v[40:43], v[168:171], v[148:151]
	v_mfma_f32_16x16x32_bf16 v[60:63], v[40:43], v[172:175], v[60:63]
	v_mfma_f32_16x16x32_bf16 v[148:151], v[36:39], v[76:79], v[152:155]
	v_mfma_f32_16x16x32_bf16 v[152:155], v[36:39], v[164:167], v[156:159]
	v_mfma_f32_16x16x32_bf16 v[156:159], v[36:39], v[168:171], v[160:163]
	v_mfma_f32_16x16x32_bf16 v[56:59], v[36:39], v[172:175], v[56:59]
	v_mfma_f32_16x16x32_bf16 v[160:163], v[32:35], v[164:167], v[68:71]
	v_mfma_f32_16x16x32_bf16 v[72:75], v[32:35], v[168:171], v[72:75]
	v_mfma_f32_16x16x32_bf16 v[164:167], v[32:35], v[172:175], v[48:51]
	v_mov_b64_e32 v[168:169], v[220:221]
	v_mov_b64_e32 v[170:171], v[222:223]
	v_mov_b64_e32 v[172:173], v[224:225]
	v_mov_b64_e32 v[174:175], v[226:227]
	v_mov_b64_e32 v[176:177], v[228:229]
	v_mov_b64_e32 v[178:179], v[230:231]
	v_mov_b64_e32 v[184:185], v[232:233]
	v_mov_b64_e32 v[186:187], v[234:235]
	v_mfma_f32_16x16x32_bf16 v[64:67], v[32:35], v[76:79], v[64:67]
	s_waitcnt vmcnt(3)
	v_mfma_f32_16x16x32_bf16 v[80:83], v[24:27], v[168:171], v[80:83]
	s_waitcnt vmcnt(2)
	v_mfma_f32_16x16x32_bf16 v[76:79], v[24:27], v[172:175], v[92:95]
	s_waitcnt vmcnt(1)
	v_mfma_f32_16x16x32_bf16 v[68:71], v[24:27], v[176:179], v[130:133]
	s_waitcnt vmcnt(0)
	v_mfma_f32_16x16x32_bf16 v[24:27], v[24:27], v[184:187], v[44:47]
	v_mfma_f32_16x16x32_bf16 v[32:35], v[28:31], v[168:171], v[52:55]
	v_mfma_f32_16x16x32_bf16 v[44:47], v[20:23], v[168:171], v[148:151]
	v_mfma_f32_16x16x32_bf16 v[48:51], v[20:23], v[172:175], v[152:155]
	v_mfma_f32_16x16x32_bf16 v[52:55], v[20:23], v[176:179], v[156:159]
	v_mfma_f32_16x16x32_bf16 v[20:23], v[20:23], v[184:187], v[56:59]
	v_mfma_f32_16x16x32_bf16 v[56:59], v[16:19], v[168:171], v[64:67]
	v_mfma_f32_16x16x32_bf16 v[64:67], v[16:19], v[176:179], v[72:75]
	s_nop 2
	v_mov_b64_e32 v[72:73], v[236:237]
	v_mov_b64_e32 v[74:75], v[238:239]
	v_mov_b64_e32 v[92:93], v[240:241]
	v_mov_b64_e32 v[94:95], v[242:243]
	s_nop 0
	v_mov_b64_e32 v[84:85], v[244:245]
	v_mov_b64_e32 v[86:87], v[246:247]
	s_nop 0
	v_mov_b64_e32 v[130:131], v[248:249]
	v_mov_b64_e32 v[132:133], v[182:183]
	v_mfma_f32_16x16x32_bf16 v[36:39], v[28:31], v[172:175], v[140:143]
	v_mfma_f32_16x16x32_bf16 v[40:43], v[28:31], v[176:179], v[144:147]
	v_mfma_f32_16x16x32_bf16 v[28:31], v[28:31], v[184:187], v[60:63]
	v_mfma_f32_16x16x32_bf16 v[60:63], v[16:19], v[172:175], v[160:163]
	s_waitcnt vmcnt(3)
	v_mfma_f32_16x16x32_bf16 v[80:83], v[12:15], v[72:75], v[80:83]
	s_waitcnt vmcnt(2)
	v_mfma_f32_16x16x32_bf16 v[76:79], v[12:15], v[92:95], v[76:79]
	s_waitcnt vmcnt(1)
	v_mfma_f32_16x16x32_bf16 v[68:71], v[12:15], v[84:87], v[68:71]
	s_waitcnt vmcnt(0)
; DI f32x4 mfma16(bf16x8 a, bf16x8 b, f32x4 c) { return __builtin_amdgcn_mfma_f32_16x16x32_bf16(a, b, c, 0, 0, 0); }
; DI void mlstm_out_unit(const Params& p, unsigned char* smem, const int tid, int u) {
;     ...
; #pragma unroll
;     for (int ni = 0; ni < 4; ++ni) {
;         const float s = sci[16 * ni + (lane & 15)];
; #pragma unroll
;         for (int mi = 0; mi < 4; ++mi) { acc[mi][ni][0] *= s; acc[mi][ni][1] *= s; acc[mi][ni][2] *= s; acc[mi][ni][3] *= s; }
;     }
;     {
;         const bf16_t* vb = vT + (((size_t)bh * 128 + c) * 256 + 64 * w + ((lane & 15) >> 2) * 8 + (lane & 3)) * 64 + (lane >> 4) * 4;
; #pragma unroll
;         for (int pr = 0; pr < 2; ++pr) {
;             bf16x8 af[4];
; #pragma unroll
;             for (int mi = 0; mi < 4; ++mi) {
;                 uint2 lo = *(const uint2*)(vb + (size_t)((mi >> 1) * 32 + (mi & 1) * 4) * 64 + pr * 32);
;                 uint2 hi = *(const uint2*)(vb + (size_t)((mi >> 1) * 32 + (mi & 1) * 4) * 64 + pr * 32 + 16);
;                 af[mi] = __builtin_bit_cast(bf16x8, make_uint4(lo.x, lo.y, hi.x, hi.y));
;             }
; #pragma unroll
;             for (int ni = 0; ni < 4; ++ni) {
;                 if (ni >= 2 * pr) {
;                     bf16x8 xb = __builtin_bit_cast(bf16x8, xs[(ni * 2 + pr) * 64 + lane]);
; #pragma unroll
;                     for (int mi = 0; mi < 4; ++mi) acc[mi][ni] = mfma16(af[mi], xb, acc[mi][ni]);
;                 }
;             }
	v_mfma_f32_16x16x32_bf16 v[140:143], v[12:15], v[130:133], v[24:27]
	v_mfma_f32_16x16x32_bf16 v[12:15], v[8:11], v[72:75], v[32:35]
	v_mfma_f32_16x16x32_bf16 v[32:35], v[8:11], v[92:95], v[36:39]
	v_mfma_f32_16x16x32_bf16 v[36:39], v[8:11], v[84:87], v[40:43]
	v_mfma_f32_16x16x32_bf16 v[40:43], v[8:11], v[130:133], v[28:31]
	s_nop 2
	ds_read2_b32 v[28:29], v123 offset0:128 offset1:144
	v_mfma_f32_16x16x32_bf16 v[16:19], v[16:19], v[184:187], v[164:167]
	s_waitcnt lgkmcnt(0)
	v_mov_b32_e32 v30, v29
	v_mfma_f32_16x16x32_bf16 v[8:11], v[4:7], v[72:75], v[44:47]
	v_mul_f32_e64 v14, v14, v28
	v_mul_f32_e64 v15, v15, v28
	v_pk_mul_f32 v[12:13], v[12:13], v[28:29] op_sel_hi:[1,0]
	v_mfma_f32_16x16x32_bf16 v[44:47], v[4:7], v[92:95], v[48:51]
	v_mfma_f32_16x16x32_bf16 v[144:147], v[4:7], v[130:133], v[20:23]
	s_nop 2
	v_mul_f32_e64 v10, v10, v28
	v_mul_f32_e64 v11, v11, v28
	v_pk_mul_f32 v[8:9], v[8:9], v[28:29] op_sel_hi:[1,0]
	v_mfma_f32_16x16x32_bf16 v[20:23], v[0:3], v[92:95], v[60:63]
	v_mfma_f32_16x16x32_bf16 v[48:51], v[4:7], v[84:87], v[52:55]
	v_mul_f32_e64 v6, v34, v30
	v_mul_f32_e64 v7, v35, v30
	v_pk_mul_f32 v[4:5], v[32:33], v[30:31] op_sel_hi:[1,0]
	s_nop 3
	v_pk_mul_f32 v[22:23], v[22:23], v[30:31] op_sel_hi:[1,0]
	v_mfma_f32_16x16x32_bf16 v[24:27], v[0:3], v[72:75], v[56:59]
	v_mul_f32_e64 v20, v20, v30
	v_mul_f32_e64 v21, v21, v30
	v_mfma_f32_16x16x32_bf16 v[52:55], v[0:3], v[84:87], v[64:67]
	v_mfma_f32_16x16x32_bf16 v[72:75], v[0:3], v[130:133], v[16:19]
	v_mul_f32_e64 v2, v78, v30
	v_mul_f32_e64 v3, v79, v30
	v_pk_mul_f32 v[0:1], v[76:77], v[30:31] op_sel_hi:[1,0]
	s_nop 0
	v_pk_mul_f32 v[26:27], v[26:27], v[28:29] op_sel_hi:[1,0]
	v_pk_mul_f32 v[18:19], v[46:47], v[30:31] op_sel_hi:[1,0]
	v_pk_mul_f32 v[16:17], v[44:45], v[30:31] op_sel_hi:[1,0]
	ds_read2_b32 v[30:31], v123 offset0:160 offset1:176
	v_pk_mul_f32 v[24:25], v[24:25], v[28:29] op_sel_hi:[1,0]
	s_waitcnt lgkmcnt(0)
	v_pk_mul_f32 v[34:35], v[70:71], v[30:31] op_sel_hi:[1,0]
	v_pk_mul_f32 v[32:33], v[68:69], v[30:31] op_sel_hi:[1,0]
	v_pk_mul_f32 v[38:39], v[38:39], v[30:31] op_sel_hi:[1,0]
	v_pk_mul_f32 v[36:37], v[36:37], v[30:31] op_sel_hi:[1,0]
	v_pk_mul_f32 v[50:51], v[50:51], v[30:31] op_sel_hi:[1,0]
	v_pk_mul_f32 v[48:49], v[48:49], v[30:31] op_sel_hi:[1,0]
	v_pk_mul_f32 v[54:55], v[54:55], v[30:31] op_sel_hi:[1,0]
	v_pk_mul_f32 v[52:53], v[52:53], v[30:31] op_sel_hi:[1,0]
	v_mov_b32_e32 v30, v31
	v_pk_mul_f32 v[58:59], v[142:143], v[30:31] op_sel_hi:[1,0]
	v_pk_mul_f32 v[56:57], v[140:141], v[30:31] op_sel_hi:[1,0]
	v_pk_mul_f32 v[62:63], v[42:43], v[30:31] op_sel_hi:[1,0]
	v_pk_mul_f32 v[60:61], v[40:41], v[30:31] op_sel_hi:[1,0]
	v_pk_mul_f32 v[66:67], v[146:147], v[30:31] op_sel_hi:[1,0]
	v_pk_mul_f32 v[64:65], v[144:145], v[30:31] op_sel_hi:[1,0]
	v_pk_mul_f32 v[70:71], v[74:75], v[30:31] op_sel_hi:[1,0]
	v_pk_mul_f32 v[68:69], v[72:73], v[30:31] op_sel_hi:[1,0]
	v_lshlrev_b64 v[30:31], 7, v[128:129]
	v_lshl_add_u64 v[88:89], v[124:125], 0, v[30:31]
	v_add_co_u32_e32 v130, vcc, s3, v88
	global_load_dwordx2 v[72:73], v[88:89], off
	global_load_dwordx2 v[74:75], v[88:89], off offset:32
	global_load_dwordx2 v[76:77], v[88:89], off offset:512
	global_load_dwordx2 v[78:79], v[88:89], off offset:544
	v_addc_co_u32_e32 v131, vcc, 0, v89, vcc
	global_load_dwordx2 v[84:85], v[130:131], off
	global_load_dwordx2 v[86:87], v[130:131], off offset:32
	global_load_dwordx2 v[92:93], v[130:131], off offset:512
	global_load_dwordx2 v[94:95], v[130:131], off offset:544
	v_pk_mul_f32 v[30:31], v[82:83], v[28:29] op_sel_hi:[1,0]
	v_pk_mul_f32 v[28:29], v[80:81], v[28:29] op_sel_hi:[1,0]
	ds_read_b128 v[80:83], v119 offset:4096
	s_waitcnt vmcnt(4) lgkmcnt(0)
	v_mfma_f32_16x16x32_bf16 v[40:43], v[76:79], v[80:83], v[12:15]
	v_mfma_f32_16x16x32_bf16 v[44:47], v[72:75], v[80:83], v[28:31]
	s_waitcnt vmcnt(2)
	v_mfma_f32_16x16x32_bf16 v[28:31], v[84:87], v[80:83], v[8:11]
	s_waitcnt vmcnt(0)
	v_mfma_f32_16x16x32_bf16 v[24:27], v[92:95], v[80:83], v[24:27]
	ds_read_b128 v[80:83], v119 offset:6144
	s_waitcnt lgkmcnt(0)
	v_mfma_f32_16x16x32_bf16 v[8:11], v[76:79], v[80:83], v[4:7]
	v_mfma_f32_16x16x32_bf16 v[4:7], v[84:87], v[80:83], v[16:19]
	s_nop 2
	ds_read_b128 v[16:19], v119 offset:8192
	v_mfma_f32_16x16x32_bf16 v[12:15], v[72:75], v[80:83], v[0:3]
	v_mfma_f32_16x16x32_bf16 v[0:3], v[92:95], v[80:83], v[20:23]
	s_waitcnt lgkmcnt(0)
; DI f32x4 mfma16(bf16x8 a, bf16x8 b, f32x4 c) { return __builtin_amdgcn_mfma_f32_16x16x32_bf16(a, b, c, 0, 0, 0); }
; DI void mlstm_out_unit(const Params& p, unsigned char* smem, const int tid, int u) {
;     ...
;             for (int ni = 0; ni < 4; ++ni) {
;                 if (ni >= 2 * pr) {
;                     bf16x8 xb = __builtin_bit_cast(bf16x8, xs[(ni * 2 + pr) * 64 + lane]);
; #pragma unroll
;                     for (int mi = 0; mi < 4; ++mi) acc[mi][ni] = mfma16(af[mi], xb, acc[mi][ni]);
;                 }
;             }
;         }
;     }
; #pragma unroll
;     for (int ni = 0; ni < 4; ++ni) {
;         const float rd = rden[16 * ni + (lane & 15)];
;         float s = 0.f;
; #pragma unroll
;         for (int mi = 0; mi < 4; ++mi) { acc[mi][ni][0] *= rd; acc[mi][ni][1] *= rd; acc[mi][ni][2] *= rd; acc[mi][ni][3] *= rd;
;             s += acc[mi][ni][0] + acc[mi][ni][1] + acc[mi][ni][2] + acc[mi][ni][3]; }
;         s += __shfl_xor(s, 16, 64); s += __shfl_xor(s, 32, 64);
;         if (lane < 16) part[w * 64 + 16 * ni + lane] = s;
;     ...
;     const float* gain = p.in[10];
;     float4 gg[2][2];
;     uint2 ogv[4][2];
;     const int ch_l = h * 256 + 64 * w + (lane >> 4) * 8;
; #pragma unroll
;     for (int k = 0; k < 2; ++k) { gg[k][0] = *(const float4*)(gain + ch_l + 32 * k); gg[k][1] = *(const float4*)(gain + ch_l + 32 * k + 4); }
; #pragma unroll
;     for (int ni = 0; ni < 4; ++ni)
; #pragma unroll
;         for (int k = 0; k < 2; ++k)
;             ogv[ni][k] = *(const uint2*)((const unsigned char*)og + ((size_t)b * 8192 + c * 64 + 16 * ni + (lane & 15)) * 1024 + ch_l + 32 * k);
	v_mfma_f32_16x16x32_bf16 v[20:23], v[72:75], v[16:19], v[32:35]
	v_mfma_f32_16x16x32_bf16 v[32:35], v[76:79], v[16:19], v[36:39]
	v_mfma_f32_16x16x32_bf16 v[36:39], v[84:87], v[16:19], v[48:51]
	s_nop 2
	ds_read_b128 v[48:51], v119 offset:10240
	v_mfma_f32_16x16x32_bf16 v[16:19], v[92:95], v[16:19], v[52:55]
	s_waitcnt lgkmcnt(0)
	v_mfma_f32_16x16x32_bf16 v[64:67], v[84:87], v[48:51], v[64:67]
	v_mfma_f32_16x16x32_bf16 v[68:71], v[92:95], v[48:51], v[68:71]
	global_load_dwordx2 v[80:81], v[88:89], off offset:64
	global_load_dwordx2 v[82:83], v[88:89], off offset:96
	global_load_dwordx2 v[84:85], v[88:89], off offset:576
	global_load_dwordx2 v[86:87], v[88:89], off offset:608
	global_load_dwordx2 v[92:93], v[130:131], off offset:64
	global_load_dwordx2 v[94:95], v[130:131], off offset:96
	global_load_dwordx2 v[128:129], v[130:131], off offset:576
	s_nop 0
	global_load_dwordx2 v[130:131], v[130:131], off offset:608
	v_mfma_f32_16x16x32_bf16 v[72:75], v[72:75], v[48:51], v[56:59]
	v_mfma_f32_16x16x32_bf16 v[76:79], v[76:79], v[48:51], v[60:63]
	ds_read_b128 v[48:51], v119 offset:9216
	s_waitcnt vmcnt(6) lgkmcnt(0)
	v_mfma_f32_16x16x32_bf16 v[60:63], v[80:83], v[48:51], v[20:23]
	s_waitcnt vmcnt(4)
	v_mfma_f32_16x16x32_bf16 v[56:59], v[84:87], v[48:51], v[32:35]
	s_waitcnt vmcnt(2)
	v_mfma_f32_16x16x32_bf16 v[52:55], v[92:95], v[48:51], v[36:39]
	s_waitcnt vmcnt(0)
	v_mfma_f32_16x16x32_bf16 v[48:51], v[128:131], v[48:51], v[16:19]
	s_nop 2
	ds_read_b128 v[16:19], v134 offset:4096
	s_waitcnt lgkmcnt(0)
	v_mfma_f32_16x16x32_bf16 v[36:39], v[80:83], v[16:19], v[72:75]
	s_nop 2
	ds_read_b32 v72, v123 offset:1280
	v_mfma_f32_16x16x32_bf16 v[32:35], v[84:87], v[16:19], v[76:79]
	v_mfma_f32_16x16x32_bf16 v[20:23], v[92:95], v[16:19], v[64:67]
	v_mfma_f32_16x16x32_bf16 v[16:19], v[128:131], v[16:19], v[68:71]
	v_readlane_b32 s76, v254, 40
	v_readlane_b32 s77, v254, 41
	v_ashrrev_i32_e32 v220, 9, v97
	v_lshlrev_b32_e32 v222, 8, v126
	s_movk_i32 s74, 0x300
	v_ashrrev_i32_e32 v221, 31, v220
	v_and_or_b32 v222, v222, s74, v136
	v_lshlrev_b64 v[220:221], 13, v[220:221]
	v_mov_b32_e32 v223, 0
	v_or_b32_e32 v220, v220, v139
	v_lshlrev_b32_e32 v226, 2, v222
	v_or_b32_e32 v220, v220, v104
	v_lshl_add_u64 v[224:225], s[72:73], 0, v[222:223]
	v_lshlrev_b64 v[220:221], 10, v[220:221]
	global_load_dwordx4 v[188:191], v226, s[76:77] offset:16
	global_load_dwordx4 v[192:195], v226, s[76:77]
	v_lshl_add_u64 v[224:225], v[224:225], 0, v[220:221]
	global_load_dwordx4 v[196:199], v226, s[76:77] offset:144
	global_load_dwordx4 v[200:203], v226, s[76:77] offset:128
	s_mov_b64 s[78:79], 0x4000
	s_mov_b64 s[80:81], 0x8000
	s_mov_b64 s[82:83], 0xc000
	v_lshl_add_u64 v[228:229], v[224:225], 0, s[78:79]
	global_load_dwordx2 v[204:205], v[224:225], off
	global_load_dwordx2 v[206:207], v[224:225], off offset:32
	v_lshl_add_u64 v[230:231], v[224:225], 0, s[80:81]
	global_load_dwordx2 v[208:209], v[228:229], off
	global_load_dwordx2 v[210:211], v[228:229], off offset:32
	v_lshl_add_u64 v[232:233], v[224:225], 0, s[82:83]
	global_load_dwordx2 v[212:213], v[230:231], off
	global_load_dwordx2 v[214:215], v[230:231], off offset:32
	global_load_dwordx2 v[216:217], v[232:233], off
	global_load_dwordx2 v[218:219], v[232:233], off offset:32
	s_waitcnt lgkmcnt(0)
	s_nop 1
	v_mul_f32_e32 v70, v45, v72
	v_fma_f32 v45, v44, v72, v70
	v_mul_f32_e32 v71, v41, v72
	v_fmac_f32_e32 v45, v46, v72
	v_fma_f32 v41, v40, v72, v71
	v_mul_f32_e32 v69, v29, v72
	v_fmac_f32_e32 v45, v47, v72
	v_fmac_f32_e32 v41, v42, v72
	v_fma_f32 v29, v28, v72, v69
	v_mul_f32_e32 v68, v25, v72
	v_add_f32_e32 v45, 0, v45
	v_fmac_f32_e32 v41, v43, v72
	v_fmac_f32_e32 v29, v30, v72
	v_fma_f32 v25, v24, v72, v68
	v_add_f32_e32 v41, v41, v45
	v_fmac_f32_e32 v29, v31, v72
	v_fmac_f32_e32 v25, v26, v72
	v_add_f32_e32 v29, v29, v41
	v_fmac_f32_e32 v25, v27, v72
	v_add_f32_e32 v25, v25, v29
	ds_bpermute_b32 v29, v90, v25
	s_waitcnt lgkmcnt(0)
	v_add_f32_e32 v25, v25, v29
	ds_bpermute_b32 v29, v91, v25
	s_and_saveexec_b64 s[86:87], s[12:13]
	s_cbranch_execz .LBB0_765
	s_waitcnt lgkmcnt(0)
	v_add_f32_e32 v25, v25, v29
	ds_write_b32 v135, v25 offset:1536
